# diff-attention block B: QK MFMA chain issued right after PV with the sum/cvt VALU in its shadows, 4th K fragment read into free registers
# baseline (speedup 1.0000x reference)
.LBB0_512:
	s_and_b32 s20, s2, 0xc000
	s_add_i32 s20, s65, s20
	v_mfma_f32_32x32x16_bf16 v[0:15], v[156:159], v[196:199], v[0:15]
	ds_read_b64_tr_b16 v[128:129], v238 offset:2048
	ds_read_b64_tr_b16 v[130:131], v238 offset:2560
	v_exp_f32_e32 v160, v96
	v_exp_f32_e32 v161, v97
	v_add_u32_e32 v152, s20, v228
	v_add_u32_e32 v239, s20, v229
	v_add_u32_e32 v240, s20, v230
	v_add_u32_e32 v241, s20, v231
	v_mfma_f32_32x32x16_bf16 v[0:15], v[162:165], v[192:195], v[0:15]
	ds_read_b64_tr_b16 v[132:133], v238 offset:3072
	ds_read_b64_tr_b16 v[134:135], v238 offset:3584
	v_exp_f32_e32 v166, v98
	v_exp_f32_e32 v167, v99
	v_mfma_f32_32x32x16_bf16 v[32:47], v[156:159], v[188:191], v[32:47]
	ds_read_b64_tr_b16 v[136:137], v238 offset:6144
	ds_read_b64_tr_b16 v[138:139], v238 offset:6656
	v_exp_f32_e32 v192, v100
	v_exp_f32_e32 v193, v101
	v_mfma_f32_32x32x16_bf16 v[32:47], v[162:165], v[184:187], v[32:47]
	ds_read_b64_tr_b16 v[140:141], v238 offset:7168
	ds_read_b64_tr_b16 v[142:143], v238 offset:7680
	v_exp_f32_e32 v188, v102
	v_exp_f32_e32 v189, v103
	v_mfma_f32_32x32x16_bf16 v[48:63], v[156:159], v[180:183], v[48:63]
	ds_read_b64_tr_b16 v[144:145], v238 offset:10240
	ds_read_b64_tr_b16 v[146:147], v238 offset:10752
	v_exp_f32_e32 v184, v104
	v_exp_f32_e32 v185, v105
	v_mfma_f32_32x32x16_bf16 v[48:63], v[162:165], v[176:179], v[48:63]
	ds_read_b64_tr_b16 v[148:149], v238 offset:11264
	ds_read_b64_tr_b16 v[150:151], v238 offset:11776
	ds_read_b128 v[180:183], v152
	v_exp_f32_e32 v186, v106
	v_exp_f32_e32 v187, v107
	v_mfma_f32_32x32x16_bf16 v[16:31], v[156:159], v[172:175], v[16:31]
	ds_read_b64_tr_b16 v[152:153], v238 offset:14336
	ds_read_b64_tr_b16 v[154:155], v238 offset:14848
	v_exp_f32_e32 v176, v108
	v_exp_f32_e32 v177, v109
	v_mfma_f32_32x32x16_bf16 v[16:31], v[162:165], v[168:171], v[16:31]
	ds_read_b64_tr_b16 v[156:157], v238 offset:15360
	ds_read_b64_tr_b16 v[158:159], v238 offset:15872
	ds_read_b128 v[168:171], v239
	ds_read_b128 v[172:175], v240
	ds_read_b128 v[250:253], v241
	v_add_f32_e32 v162, v166, v160
	v_add_f32_e32 v163, v167, v161
	v_exp_f32_e32 v178, v110
	v_exp_f32_e32 v179, v111
	s_waitcnt lgkmcnt(7)
	v_mfma_f32_32x32x16_bf16 v[80:95], v[180:183], v[112:115], v[64:79]
	v_pk_add_f32 v[164:165], v[192:193], v[162:163]
	v_pk_add_f32 v[164:165], v[188:189], v[164:165]
	v_cvt_pk_bf16_f32 v160, v160, v161
	v_cvt_pk_bf16_f32 v161, v166, v167
	s_waitcnt lgkmcnt(2)
	v_mfma_f32_32x32x16_bf16 v[80:95], v[168:171], v[116:119], v[80:95]
	v_pk_add_f32 v[166:167], v[184:185], v[164:165]
	v_cvt_pk_bf16_f32 v162, v192, v193
	v_pk_add_f32 v[166:167], v[186:187], v[166:167]
	v_cvt_pk_bf16_f32 v163, v188, v189
	s_waitcnt lgkmcnt(1)
	v_mfma_f32_32x32x16_bf16 v[80:95], v[172:175], v[120:123], v[80:95]
	v_cvt_pk_bf16_f32 v164, v184, v185
	v_cvt_pk_bf16_f32 v165, v186, v187
	v_pk_add_f32 v[184:185], v[176:177], v[166:167]
	v_cvt_pk_bf16_f32 v166, v176, v177
	v_cvt_pk_bf16_f32 v167, v178, v179
	s_waitcnt lgkmcnt(0)
	v_mfma_f32_32x32x16_bf16 v[80:95], v[250:253], v[124:127], v[80:95]
	v_pk_add_f32 v[176:177], v[178:179], v[184:185]
	v_max3_f32 v178, v96, v97, v98
	v_max3_f32 v100, v99, v100, v101
	v_add_f32_e32 v96, v176, v177
	v_add_f32_e32 v235, v235, v96
	v_max3_f32 v101, v178, v102, v103
	v_max3_f32 v100, v100, v104, v105
	v_max3_f32 v101, v101, v106, v107
	v_max3_f32 v100, v100, v108, v109
	v_max3_f32 v101, v101, v110, v111
	v_max_f32_e32 v100, v101, v100
	ds_bpermute_b32 v101, v214, v100
	s_waitcnt lgkmcnt(0)
	v_max_f32_e32 v96, v100, v101
	s_addk_i32 s2, 0x4000
	s_add_i32 s3, s3, -1
	s_cmp_ge_u32 s37, s84
	s_cbranch_scc1 .LBB0_527
	s_mov_b32 s76, s37
	s_branch .LBB0_502
